# single-round GEMM phases (P4a/P4b/P5/P8): every workgroup that owns a split-K tail item runs it before its GEMM tile; plus in-flight counter loads in the first grid barrier
# baseline (speedup 1.0000x reference)
; #define LAS __attribute__((address_space(3)))
; __device__ __forceinline__ int opaque_tid() { int t = threadIdx.x; asm volatile("" : "+v"(t)); return t; }
; #define PG8_BAR __builtin_amdgcn_s_barrier()
; template <class Epi>
; __device__ __forceinline__ void gemm_phase(LAS unsigned char* lds, const Gemm g, const StaticOrder& S, const Epi& E) {
;     const int tid = opaque_tid(), wid = __builtin_amdgcn_readfirstlane(tid >> 6), lane = tid & 63, wr = wid >> 2, wc = wid & 3, fr = lane & 15, fq = lane >> 4;
;     const int K = g.K, nt = K / BK;
;     unsigned voffA[2], voffB[2];
; #pragma unroll
;     for (int i = 0; i < 2; ++i) { int R, C; stage_rc(tid * 16 + i * 8192, R, C); const int Rb = Epi::PERM ? ((R & ~31) + perm32(R & 31)) : R;
;         voffA[i] = (unsigned)(R * K + C) * 2u; voffB[i] = (unsigned)(Rb * K + C) * 2u; }
;     const size_t kstep = (size_t)(BK * 2);
;     const size_t hstep = (size_t)HALF * K * 2;
;     const size_t tstep = 2 * hstep;
;     const unsigned ldsw = (unsigned)wid * 1024u;
;     const int aoff = lds_byte(wr * 64 + fr, fq * 8), boff = lds_byte(wc * 32 + fr, fq * 8);
;     ...
;     Unit cur, nxt; int ui = 0;
;     if (!S.next(0, cur)) return;
;     f32x4 acc[2][2][4][2];
; #pragma unroll
;     for (int a = 0; a < 2; ++a)
; #pragma unroll
;         for (int b = 0; b < 2; ++b)
; #pragma unroll
;             for (int m = 0; m < 4; ++m)
; #pragma unroll
;                 for (int n = 0; n < 2; ++n) acc[a][b][m][n] = (f32x4){0.f, 0.f, 0.f, 0.f};
;     bf16x8 At[4][2], B0[2][2], B1[2][2];
;     const char* cA = (const char*)g.A + (size_t)cur.pm * tstep; const char* cB = (const char*)g.Bt + (size_t)cur.pn * tstep;
;     PG8_STAGE(PG8_SB(0, 0), cB, voffB); PG8_STAGE(PG8_SB(0, 1), cB + hstep, voffB); PG8_STAGE(PG8_SA(0, 0), cA, voffA); PG8_STAGE(PG8_SA(0, 1), cA + hstep, voffA);
;     if (wr == 1) PG8_BAR;
; __global__ void __launch_bounds__(512, 2) mega(Params KP) {
;     ...
;               pg8::Gemm g{(const bf16_t*)(ws + WS_HG), (const bf16_t*)(ws + WS_WA) + (size_t)l * D * D, MM, D, D}; EpiYa E{(bf16_t*)(ws + WS_T), (const bf16_t*)(ws + WS_Z)}; { int np = 2; asm volatile("" : "+s"(np)); for (int pass = 0; pass < np; ++pass) { if ((pass == 0) == ((bid & 1) != 0)) tail_splitk<2, 4>(lds, g.A, g.Bt, D, MM, 8, 0, 16, 0, E); else pg8::gemm_phase<EpiYa>(lds, g, S, E); } } }
.LBB0_692:
	s_cmp_lg_u32 s74, 0
	s_cselect_b64 s[0:1], -1, 0
	v_cndmask_b32_e64 v0, 0, 1, s[0:1]
	v_mov_b32_e32 v2, 1
	v_cmp_eq_u32_e32 vcc, v0, v2
	s_mov_b64 s[0:1], -1
	s_cbranch_vccz .LBB0_714
	v_mov_b32_e32 v8, v188
	s_andn2_b64 vcc, exec, s[42:43]
	v_readfirstlane_b32 s4, v8
	s_cbranch_vccnz .LBB0_713
	v_lshlrev_b32_e32 v0, 4, v8
	v_add_u32_e32 v3, 0x2000, v0
	v_ashrrev_i32_e32 v2, 31, v3
	v_lshrrev_b32_e32 v2, 22, v2
	v_add_u32_e32 v2, v3, v2
	v_ashrrev_i32_e32 v2, 10, v2
	v_lshlrev_b32_e32 v4, 5, v2
	v_and_b32_e32 v5, 32, v4
	v_mul_i32_i24_e32 v4, 0x400, v2
	v_sub_u32_e32 v3, v3, v4
	v_lshrrev_b32_e32 v4, 4, v3
	v_bitop3_b32 v4, v4, v3, 32 bitop3:0x6c
	v_ashrrev_i32_e32 v3, 31, v4
	v_lshrrev_b32_e32 v3, 26, v3
	v_add_u32_e32 v6, v4, v3
	v_ashrrev_i32_e32 v3, 6, v6
	v_and_b32_e32 v6, 0xc0, v6
	v_sub_u32_e32 v4, v4, v6
	v_ashrrev_i16_sdwa v4, v191, sext(v4) dst_sel:DWORD dst_unused:UNUSED_PAD src0_sel:DWORD src1_sel:BYTE_0
	v_lshlrev_b32_e32 v6, 3, v2
	v_bfe_i32 v4, v4, 0, 16
	v_and_b32_e32 v6, 0x1ffff0, v6
	v_add_u32_e32 v5, v5, v4
	v_add_lshl_u32 v6, v3, v6, 11
	s_waitcnt vmcnt(0)
	v_lshl_add_u32 v142, v5, 1, v6
	v_ashrrev_i32_e32 v5, 31, v8
	v_lshrrev_b32_e32 v5, 26, v5
	v_add_u32_e32 v5, v8, v5
	v_ashrrev_i32_e32 v5, 6, v5
	v_lshlrev_b32_e32 v6, 5, v5
	v_and_b32_e32 v9, 32, v6
	v_bfe_i32 v6, v8, 27, 1
	v_lshrrev_b32_e32 v6, 22, v6
	v_add_u32_e32 v6, v0, v6
	v_and_b32_e32 v6, 0xfffffc00, v6
	v_sub_u32_e32 v0, v0, v6
	v_lshrrev_b32_e32 v6, 4, v0
	v_bitop3_b32 v7, v6, v0, 32 bitop3:0x6c
	v_ashrrev_i32_e32 v0, 31, v0
	v_lshrrev_b32_e32 v0, 26, v0
	v_add_u32_e32 v0, v7, v0
	v_ashrrev_i32_e32 v6, 6, v0
	v_mul_i32_i24_e32 v0, 64, v6
	v_sub_u32_e32 v0, v7, v0
	v_ashrrev_i16_sdwa v0, v191, sext(v0) dst_sel:DWORD dst_unused:UNUSED_PAD src0_sel:DWORD src1_sel:BYTE_0
	v_bfe_i32 v7, v0, 0, 16
	s_ashr_i32 s5, s4, 6
	v_add_u32_e32 v0, v9, v7
	v_lshlrev_b32_e32 v9, 3, v5
	s_lshl_b32 s45, s5, 10
	v_and_b32_e32 v9, 0x1ffff0, v9
	v_add_lshl_u32 v9, v6, v9, 11
	s_add_i32 s76, s45, 0
	v_lshl_add_u32 v0, v0, 1, v9
	s_add_i32 m0, s76, 0x10000
	s_add_i32 s77, s76, 0x2000
	global_load_lds_dwordx4 v0, s[46:47]
	s_add_i32 m0, s76, 0x12000
	s_add_i32 s78, s76, 0x4000
	global_load_lds_dwordx4 v142, s[46:47]
	s_add_i32 m0, s76, 0x14000
	s_add_i32 s79, s76, 0x6000
	global_load_lds_dwordx4 v0, s[48:49]
	s_add_i32 m0, s76, 0x16000
	s_ashr_i32 s12, s4, 8
	global_load_lds_dwordx4 v142, s[48:49]
	s_mov_b32 m0, s76
	s_cmp_eq_u32 s12, 1
	global_load_lds_dwordx4 v0, s[50:51]
	s_mov_b32 m0, s77
	s_cselect_b64 s[0:1], -1, 0
	global_load_lds_dwordx4 v142, s[50:51]
	s_mov_b32 m0, s78
	s_cmp_lg_u32 s12, 1
	global_load_lds_dwordx4 v0, s[52:53]
	s_mov_b32 m0, s79
	s_nop 0
	global_load_lds_dwordx4 v142, s[52:53]
	s_cbranch_scc1 .LBB0_696
	s_barrier

; #define LAS __attribute__((address_space(3)))
; __device__ __forceinline__ int opaque_tid() { int t = threadIdx.x; asm volatile("" : "+v"(t)); return t; }
; #define PG8_BAR __builtin_amdgcn_s_barrier()
; template <class Epi>
; __device__ __forceinline__ void gemm_phase(LAS unsigned char* lds, const Gemm g, const StaticOrder& S, const Epi& E) {
;     const int tid = opaque_tid(), wid = __builtin_amdgcn_readfirstlane(tid >> 6), lane = tid & 63, wr = wid >> 2, wc = wid & 3, fr = lane & 15, fq = lane >> 4;
;     const int K = g.K, nt = K / BK;
;     unsigned voffA[2], voffB[2];
; #pragma unroll
;     for (int i = 0; i < 2; ++i) { int R, C; stage_rc(tid * 16 + i * 8192, R, C); const int Rb = Epi::PERM ? ((R & ~31) + perm32(R & 31)) : R;
;         voffA[i] = (unsigned)(R * K + C) * 2u; voffB[i] = (unsigned)(Rb * K + C) * 2u; }
;     const size_t kstep = (size_t)(BK * 2);
;     const size_t hstep = (size_t)HALF * K * 2;
;     const size_t tstep = 2 * hstep;
;     const unsigned ldsw = (unsigned)wid * 1024u;
;     const int aoff = lds_byte(wr * 64 + fr, fq * 8), boff = lds_byte(wc * 32 + fr, fq * 8);
;     ...
;     Unit cur, nxt; int ui = 0;
;     if (!S.next(0, cur)) return;
;     f32x4 acc[2][2][4][2];
; #pragma unroll
;     for (int a = 0; a < 2; ++a)
; #pragma unroll
;         for (int b = 0; b < 2; ++b)
; #pragma unroll
;             for (int m = 0; m < 4; ++m)
; #pragma unroll
;                 for (int n = 0; n < 2; ++n) acc[a][b][m][n] = (f32x4){0.f, 0.f, 0.f, 0.f};
;     bf16x8 At[4][2], B0[2][2], B1[2][2];
;     const char* cA = (const char*)g.A + (size_t)cur.pm * tstep; const char* cB = (const char*)g.Bt + (size_t)cur.pn * tstep;
;     PG8_STAGE(PG8_SB(0, 0), cB, voffB); PG8_STAGE(PG8_SB(0, 1), cB + hstep, voffB); PG8_STAGE(PG8_SA(0, 0), cA, voffA); PG8_STAGE(PG8_SA(0, 1), cA + hstep, voffA);
;     if (wr == 1) PG8_BAR;
; __global__ void __launch_bounds__(512, 2) mega(Params KP) {
;     ...
;               pg8::Gemm g{(const bf16_t*)(ws + WS_OG), (const bf16_t*)(ws + WS_WB) + (size_t)l * D * D, MM, D, D}; EpiMerge E{(const bf16_t*)(ws + WS_T), (const bf16_t*)(ws + WS_Z), (bf16_t*)(ws + WS_MG)}; { int np = 2; asm volatile("" : "+s"(np)); for (int pass = 0; pass < np; ++pass) { if ((pass == 0) == ((bid & 1) != 0)) tail_splitk<2, 4>(lds, g.A, g.Bt, D, MM, 8, 0, 16, 0, E); else pg8::gemm_phase<EpiMerge>(lds, g, S, E); } } } }
.LBB0_776:
	s_cmp_lg_u32 s75, 0
	s_cselect_b64 s[0:1], -1, 0
	v_cndmask_b32_e64 v0, 0, 1, s[0:1]
	v_mov_b32_e32 v2, 1
	v_cmp_eq_u32_e32 vcc, v0, v2
	s_mov_b64 s[0:1], -1
	s_cbranch_vccz .LBB0_798
	v_mov_b32_e32 v8, v188
	s_andn2_b64 vcc, exec, s[52:53]
	v_readfirstlane_b32 s4, v8
	s_cbranch_vccnz .LBB0_797
	v_lshlrev_b32_e32 v0, 4, v8
	v_add_u32_e32 v3, 0x2000, v0
	v_ashrrev_i32_e32 v2, 31, v3
	v_lshrrev_b32_e32 v2, 22, v2
	v_add_u32_e32 v2, v3, v2
	v_ashrrev_i32_e32 v2, 10, v2
	v_lshlrev_b32_e32 v4, 5, v2
	v_and_b32_e32 v5, 32, v4
	v_mul_i32_i24_e32 v4, 0x400, v2
	v_sub_u32_e32 v3, v3, v4
	v_lshrrev_b32_e32 v4, 4, v3
	v_bitop3_b32 v4, v4, v3, 32 bitop3:0x6c
	v_ashrrev_i32_e32 v3, 31, v4
	v_lshrrev_b32_e32 v3, 26, v3
	v_add_u32_e32 v6, v4, v3
	v_ashrrev_i32_e32 v3, 6, v6
	v_and_b32_e32 v6, 0xc0, v6
	v_sub_u32_e32 v4, v4, v6
	v_ashrrev_i16_sdwa v4, v191, sext(v4) dst_sel:DWORD dst_unused:UNUSED_PAD src0_sel:DWORD src1_sel:BYTE_0
	v_lshlrev_b32_e32 v6, 3, v2
	v_bfe_i32 v4, v4, 0, 16
	v_and_b32_e32 v6, 0x1ffff0, v6
	v_add_u32_e32 v5, v5, v4
	v_add_lshl_u32 v6, v3, v6, 11
	s_waitcnt vmcnt(0)
	v_lshl_add_u32 v142, v5, 1, v6
	v_ashrrev_i32_e32 v5, 31, v8
	v_lshrrev_b32_e32 v5, 26, v5
	v_add_u32_e32 v5, v8, v5
	v_ashrrev_i32_e32 v5, 6, v5
	v_lshlrev_b32_e32 v6, 5, v5
	v_and_b32_e32 v9, 32, v6
	v_bfe_i32 v6, v8, 27, 1
	v_lshrrev_b32_e32 v6, 22, v6
	v_add_u32_e32 v6, v0, v6
	v_and_b32_e32 v6, 0xfffffc00, v6
	v_sub_u32_e32 v0, v0, v6
	v_lshrrev_b32_e32 v6, 4, v0
	v_bitop3_b32 v7, v6, v0, 32 bitop3:0x6c
	v_ashrrev_i32_e32 v0, 31, v0
	v_lshrrev_b32_e32 v0, 26, v0
	v_add_u32_e32 v0, v7, v0
	v_ashrrev_i32_e32 v6, 6, v0
	v_mul_i32_i24_e32 v0, 64, v6
	v_sub_u32_e32 v0, v7, v0
	v_ashrrev_i16_sdwa v0, v191, sext(v0) dst_sel:DWORD dst_unused:UNUSED_PAD src0_sel:DWORD src1_sel:BYTE_0
	v_bfe_i32 v7, v0, 0, 16
	s_ashr_i32 s5, s4, 6
	v_add_u32_e32 v0, v9, v7
	v_lshlrev_b32_e32 v9, 3, v5
	s_lshl_b32 s55, s5, 10
	v_and_b32_e32 v9, 0x1ffff0, v9
	v_add_lshl_u32 v9, v6, v9, 11
	s_add_i32 s77, s55, 0
	v_lshl_add_u32 v0, v0, 1, v9
	s_add_i32 m0, s77, 0x10000
	s_add_i32 s78, s77, 0x2000
	global_load_lds_dwordx4 v0, s[56:57]
	s_add_i32 m0, s77, 0x12000
	s_add_i32 s79, s77, 0x4000
	global_load_lds_dwordx4 v142, s[56:57]
	s_add_i32 m0, s77, 0x14000
	s_add_i32 s80, s77, 0x6000
	global_load_lds_dwordx4 v0, s[34:35]
	s_add_i32 m0, s77, 0x16000
	s_ashr_i32 s12, s4, 8
	global_load_lds_dwordx4 v142, s[34:35]
	s_mov_b32 m0, s77
	s_cmp_eq_u32 s12, 1
	global_load_lds_dwordx4 v0, s[10:11]
	s_mov_b32 m0, s78
	s_cselect_b64 s[0:1], -1, 0
	global_load_lds_dwordx4 v142, s[10:11]
	s_mov_b32 m0, s79
	s_cmp_lg_u32 s12, 1
	global_load_lds_dwordx4 v0, s[44:45]
	s_mov_b32 m0, s80
	s_nop 0
	global_load_lds_dwordx4 v142, s[44:45]
	s_cbranch_scc1 .LBB0_780
	s_barrier

; #define LAS __attribute__((address_space(3)))
; __device__ __forceinline__ int opaque_tid() { int t = threadIdx.x; asm volatile("" : "+v"(t)); return t; }
; #define PG8_BAR __builtin_amdgcn_s_barrier()
; template <class Epi>
; __device__ __forceinline__ void gemm_phase(LAS unsigned char* lds, const Gemm g, const StaticOrder& S, const Epi& E) {
;     const int tid = opaque_tid(), wid = __builtin_amdgcn_readfirstlane(tid >> 6), lane = tid & 63, wr = wid >> 2, wc = wid & 3, fr = lane & 15, fq = lane >> 4;
;     const int K = g.K, nt = K / BK;
;     unsigned voffA[2], voffB[2];
; #pragma unroll
;     for (int i = 0; i < 2; ++i) { int R, C; stage_rc(tid * 16 + i * 8192, R, C); const int Rb = Epi::PERM ? ((R & ~31) + perm32(R & 31)) : R;
;         voffA[i] = (unsigned)(R * K + C) * 2u; voffB[i] = (unsigned)(Rb * K + C) * 2u; }
;     const size_t kstep = (size_t)(BK * 2);
;     const size_t hstep = (size_t)HALF * K * 2;
;     const size_t tstep = 2 * hstep;
;     const unsigned ldsw = (unsigned)wid * 1024u;
;     const int aoff = lds_byte(wr * 64 + fr, fq * 8), boff = lds_byte(wc * 32 + fr, fq * 8);
;     ...
;     Unit cur, nxt; int ui = 0;
;     if (!S.next(0, cur)) return;
;     f32x4 acc[2][2][4][2];
; #pragma unroll
;     for (int a = 0; a < 2; ++a)
; #pragma unroll
;         for (int b = 0; b < 2; ++b)
; #pragma unroll
;             for (int m = 0; m < 4; ++m)
; #pragma unroll
;                 for (int n = 0; n < 2; ++n) acc[a][b][m][n] = (f32x4){0.f, 0.f, 0.f, 0.f};
;     bf16x8 At[4][2], B0[2][2], B1[2][2];
;     const char* cA = (const char*)g.A + (size_t)cur.pm * tstep; const char* cB = (const char*)g.Bt + (size_t)cur.pn * tstep;
;     PG8_STAGE(PG8_SB(0, 0), cB, voffB); PG8_STAGE(PG8_SB(0, 1), cB + hstep, voffB); PG8_STAGE(PG8_SA(0, 0), cA, voffA); PG8_STAGE(PG8_SA(0, 1), cA + hstep, voffA);
;     if (wr == 1) PG8_BAR;
; __global__ void __launch_bounds__(512, 2) mega(Params KP) {
;     ...
;             EpiResid E{(bf16_t*)(ws + WS_XB), (float*)(ws + WS_SS) + (size_t)M * 16}; { int np = 2; asm volatile("" : "+s"(np)); for (int pass = 0; pass < np; ++pass) { if ((pass == 0) == ((bid & 1) != 0)) tail_splitk<2, 4>(lds, g.A, g.Bt, D, MM, 8, 0, 16, 0, E); else pg8::gemm_phase<EpiResid>(lds, g, S, E); } } }
.LBB0_864:
	s_cmp_lg_u32 s80, 0
	s_cselect_b64 s[0:1], -1, 0
	v_cndmask_b32_e64 v0, 0, 1, s[0:1]
	s_waitcnt vmcnt(0) lgkmcnt(0)
	v_mov_b32_e32 v2, 1
	v_cmp_eq_u32_e32 vcc, v0, v2
	s_mov_b64 s[0:1], -1
	s_cbranch_vccz .LBB0_902
	v_mov_b32_e32 v10, v188
	s_andn2_b64 vcc, exec, s[34:35]
	v_readfirstlane_b32 s4, v10
	s_cbranch_vccnz .LBB0_901
	v_lshlrev_b32_e32 v0, 4, v10
	v_add_u32_e32 v3, 0x2000, v0
	v_ashrrev_i32_e32 v2, 31, v3
	v_lshrrev_b32_e32 v2, 22, v2
	v_add_u32_e32 v2, v3, v2
	v_ashrrev_i32_e32 v2, 10, v2
	v_mul_i32_i24_e32 v4, 0x400, v2
	v_sub_u32_e32 v3, v3, v4
	v_lshrrev_b32_e32 v4, 4, v3
	v_bitop3_b32 v5, v4, v3, 32 bitop3:0x6c
	v_ashrrev_i32_e32 v3, 31, v5
	v_lshrrev_b32_e32 v3, 26, v3
	v_add_u32_e32 v6, v5, v3
	v_ashrrev_i32_e32 v3, 6, v6
	v_and_b32_e32 v6, 0xc0, v6
	v_sub_u32_e32 v5, v5, v6
	v_bfe_i32 v6, v10, 27, 1
	v_lshrrev_b32_e32 v6, 22, v6
	v_add_u32_e32 v6, v0, v6
	v_and_b32_e32 v6, 0xfffffc00, v6
	v_sub_u32_e32 v0, v0, v6
	v_lshrrev_b32_e32 v6, 4, v0
	v_bitop3_b32 v9, v6, v0, 32 bitop3:0x6c
	v_ashrrev_i32_e32 v0, 31, v0
	v_lshlrev_b32_e32 v4, 3, v2
	v_lshrrev_b32_e32 v0, 26, v0
	v_and_b32_e32 v4, 0x1ffff0, v4
	v_add_u32_e32 v0, v9, v0
	v_add_u32_e32 v7, v3, v4
	v_lshlrev_b32_e32 v4, 5, v2
	v_ashrrev_i32_e32 v6, 6, v0
	v_ashrrev_i32_e32 v0, 31, v10
	v_and_b32_e32 v4, 32, v4
	v_ashrrev_i16_sdwa v5, v191, sext(v5) dst_sel:DWORD dst_unused:UNUSED_PAD src0_sel:DWORD src1_sel:BYTE_0
	v_lshrrev_b32_e32 v0, 26, v0
	v_lshl_or_b32 v7, v7, 10, v4
	v_bfe_i32 v5, v5, 0, 16
	v_add_u32_e32 v0, v10, v0
	s_waitcnt vmcnt(0)
	v_add_lshl_u32 v142, v7, v5, 1
	v_ashrrev_i32_e32 v7, 6, v0
	v_lshlrev_b32_e32 v0, 3, v7
	v_mul_i32_i24_e32 v11, 64, v6
	s_ashr_i32 s5, s4, 6
	v_and_b32_e32 v0, 0x1ffff0, v0
	v_lshlrev_b32_e32 v8, 5, v7
	v_sub_u32_e32 v9, v9, v11
	s_lshl_b32 s43, s5, 10
	v_add_u32_e32 v0, v6, v0
	v_and_b32_e32 v8, 32, v8
	v_ashrrev_i16_sdwa v9, v191, sext(v9) dst_sel:DWORD dst_unused:UNUSED_PAD src0_sel:DWORD src1_sel:BYTE_0
	v_lshl_or_b32 v0, v0, 10, v8
	v_bfe_i32 v9, v9, 0, 16
	s_add_i32 s82, s43, 0
	v_add_lshl_u32 v0, v0, v9, 1
	s_add_i32 m0, s82, 0x10000
	s_add_i32 s83, s82, 0x2000
	global_load_lds_dwordx4 v0, s[44:45]
	s_add_i32 m0, s82, 0x12000
	s_add_i32 s84, s82, 0x4000
	global_load_lds_dwordx4 v142, s[44:45]
	s_add_i32 m0, s82, 0x14000
	s_add_i32 s85, s82, 0x6000
	global_load_lds_dwordx4 v0, s[46:47]
	s_add_i32 m0, s82, 0x16000
	s_ashr_i32 s30, s4, 8
	global_load_lds_dwordx4 v142, s[46:47]
	s_mov_b32 m0, s82
	s_cmp_eq_u32 s30, 1
	global_load_lds_dwordx4 v0, s[48:49]
	s_mov_b32 m0, s83
	s_cselect_b64 s[0:1], -1, 0
	global_load_lds_dwordx4 v142, s[48:49]
	s_mov_b32 m0, s84
	s_cmp_lg_u32 s30, 1
	global_load_lds_dwordx4 v0, s[50:51]
	s_mov_b32 m0, s85
	s_nop 0
	global_load_lds_dwordx4 v142, s[50:51]
	s_cbranch_scc1 .LBB0_868
	s_barrier

; #define LAS __attribute__((address_space(3)))
; __device__ __forceinline__ int opaque_tid() { int t = threadIdx.x; asm volatile("" : "+v"(t)); return t; }
; #define PG8_BAR __builtin_amdgcn_s_barrier()
; template <class Epi>
; __device__ __forceinline__ void gemm_phase(LAS unsigned char* lds, const Gemm g, const StaticOrder& S, const Epi& E) {
;     const int tid = opaque_tid(), wid = __builtin_amdgcn_readfirstlane(tid >> 6), lane = tid & 63, wr = wid >> 2, wc = wid & 3, fr = lane & 15, fq = lane >> 4;
;     const int K = g.K, nt = K / BK;
;     unsigned voffA[2], voffB[2];
; #pragma unroll
;     for (int i = 0; i < 2; ++i) { int R, C; stage_rc(tid * 16 + i * 8192, R, C); const int Rb = Epi::PERM ? ((R & ~31) + perm32(R & 31)) : R;
;         voffA[i] = (unsigned)(R * K + C) * 2u; voffB[i] = (unsigned)(Rb * K + C) * 2u; }
;     const size_t kstep = (size_t)(BK * 2);
;     const size_t hstep = (size_t)HALF * K * 2;
;     const size_t tstep = 2 * hstep;
;     const unsigned ldsw = (unsigned)wid * 1024u;
;     const int aoff = lds_byte(wr * 64 + fr, fq * 8), boff = lds_byte(wc * 32 + fr, fq * 8);
;     ...
;     Unit cur, nxt; int ui = 0;
;     if (!S.next(0, cur)) return;
;     f32x4 acc[2][2][4][2];
; #pragma unroll
;     for (int a = 0; a < 2; ++a)
; #pragma unroll
;         for (int b = 0; b < 2; ++b)
; #pragma unroll
;             for (int m = 0; m < 4; ++m)
; #pragma unroll
;                 for (int n = 0; n < 2; ++n) acc[a][b][m][n] = (f32x4){0.f, 0.f, 0.f, 0.f};
;     bf16x8 At[4][2], B0[2][2], B1[2][2];
;     const char* cA = (const char*)g.A + (size_t)cur.pm * tstep; const char* cB = (const char*)g.Bt + (size_t)cur.pn * tstep;
;     PG8_STAGE(PG8_SB(0, 0), cB, voffB); PG8_STAGE(PG8_SB(0, 1), cB + hstep, voffB); PG8_STAGE(PG8_SA(0, 0), cA, voffA); PG8_STAGE(PG8_SA(0, 1), cA + hstep, voffA);
;     if (wr == 1) PG8_BAR;
; __global__ void __launch_bounds__(512, 2) mega(Params KP) {
;     ...
;             EpiResid E{(bf16_t*)(ws + WS_XB), (float*)(ws + WS_SS)}; { int np = 2; asm volatile("" : "+s"(np)); for (int pass = 0; pass < np; ++pass) { if ((pass == 0) == ((bid & 1) != 0)) tail_splitk<2, 4>(lds, g.A, g.Bt, DFF, MM, 8, 0, 16, 0, E); else pg8::gemm_phase<EpiResid>(lds, g, S, E); } } }
.LBB0_1122:
	s_cmp_lg_u32 s78, 0
	s_cselect_b64 s[0:1], -1, 0
	v_cndmask_b32_e64 v0, 0, 1, s[0:1]
	s_waitcnt vmcnt(0) lgkmcnt(0)
	v_mov_b32_e32 v2, 1
	v_cmp_eq_u32_e32 vcc, v0, v2
	s_mov_b64 s[0:1], -1
	s_cbranch_vccz .LBB0_1164
	v_mov_b32_e32 v10, v188
	s_andn2_b64 vcc, exec, s[28:29]
	v_readfirstlane_b32 s0, v10
	s_cbranch_vccnz .LBB0_1163
	v_lshlrev_b32_e32 v0, 4, v10
	v_add_u32_e32 v3, 0x2000, v0
	v_ashrrev_i32_e32 v2, 31, v3
	v_lshrrev_b32_e32 v2, 22, v2
	v_add_u32_e32 v2, v3, v2
	v_ashrrev_i32_e32 v2, 10, v2
	v_mul_i32_i24_e32 v4, 0x400, v2
	v_sub_u32_e32 v3, v3, v4
	v_lshrrev_b32_e32 v4, 4, v3
	v_bitop3_b32 v5, v4, v3, 32 bitop3:0x6c
	v_ashrrev_i32_e32 v3, 31, v5
	v_lshrrev_b32_e32 v3, 26, v3
	v_add_u32_e32 v6, v5, v3
	v_ashrrev_i32_e32 v3, 6, v6
	v_and_b32_e32 v6, 0xc0, v6
	v_sub_u32_e32 v5, v5, v6
	v_bfe_i32 v6, v10, 27, 1
	v_lshrrev_b32_e32 v6, 22, v6
	v_add_u32_e32 v6, v0, v6
	v_and_b32_e32 v6, 0xfffffc00, v6
	v_sub_u32_e32 v0, v0, v6
	v_lshrrev_b32_e32 v6, 4, v0
	v_lshlrev_b32_e32 v4, 3, v2
	v_bitop3_b32 v9, v6, v0, 32 bitop3:0x6c
	v_ashrrev_i32_e32 v0, 31, v0
	v_and_b32_e32 v4, 0x3ffff0, v4
	v_lshrrev_b32_e32 v0, 26, v0
	v_add_u32_e32 v4, v3, v4
	s_movk_i32 s4, 0xc00
	v_add_u32_e32 v0, v9, v0
	v_mul_lo_u32 v7, v4, s4
	v_lshlrev_b32_e32 v4, 5, v2
	v_ashrrev_i32_e32 v6, 6, v0
	v_ashrrev_i32_e32 v0, 31, v10
	v_and_b32_e32 v4, 32, v4
	v_ashrrev_i16_sdwa v5, v191, sext(v5) dst_sel:DWORD dst_unused:UNUSED_PAD src0_sel:DWORD src1_sel:BYTE_0
	v_lshrrev_b32_e32 v0, 26, v0
	v_or_b32_e32 v7, v7, v4
	v_bfe_i32 v5, v5, 0, 16
	v_add_u32_e32 v0, v10, v0
	v_add_lshl_u32 v142, v7, v5, 1
	v_ashrrev_i32_e32 v7, 6, v0
	v_lshlrev_b32_e32 v0, 3, v7
	v_and_b32_e32 v0, 0x3ffff0, v0
	v_mul_i32_i24_e32 v11, 64, v6
	s_ashr_i32 s1, s0, 6
	v_add_u32_e32 v0, v6, v0
	v_lshlrev_b32_e32 v8, 5, v7
	v_sub_u32_e32 v9, v9, v11
	s_lshl_b32 s81, s1, 10
	v_mul_lo_u32 v0, v0, s4
	v_and_b32_e32 v8, 32, v8
	v_ashrrev_i16_sdwa v9, v191, sext(v9) dst_sel:DWORD dst_unused:UNUSED_PAD src0_sel:DWORD src1_sel:BYTE_0
	v_or_b32_e32 v0, v0, v8
	v_bfe_i32 v9, v9, 0, 16
	s_add_i32 s82, s81, 0
	v_add_lshl_u32 v0, v0, v9, 1
	s_add_i32 m0, s82, 0x10000
	s_add_i32 s83, s82, 0x2000
	global_load_lds_dwordx4 v0, s[34:35]
	s_add_i32 m0, s82, 0x12000
	s_add_i32 s84, s82, 0x4000
	global_load_lds_dwordx4 v142, s[34:35]
	s_add_i32 m0, s82, 0x14000
	s_add_i32 s85, s82, 0x6000
	global_load_lds_dwordx4 v0, s[42:43]
	s_add_i32 m0, s82, 0x16000
	s_ashr_i32 s4, s0, 8
	global_load_lds_dwordx4 v142, s[42:43]
	s_mov_b32 m0, s82
	s_cmp_eq_u32 s4, 1
	global_load_lds_dwordx4 v0, s[44:45]
	s_mov_b32 m0, s83
	s_cselect_b64 s[52:53], -1, 0
	global_load_lds_dwordx4 v142, s[44:45]
	s_mov_b32 m0, s84
	s_cmp_lg_u32 s4, 1
	global_load_lds_dwordx4 v0, s[46:47]
	s_mov_b32 m0, s85
	s_nop 0
	global_load_lds_dwordx4 v142, s[46:47]
	s_cbranch_scc1 .LBB0_1126
	s_barrier
